# comb7: row phases keep plain stores + leader wbl2 in their 4 barriers (other phases sc1 write-through, no wbl2)
# baseline (speedup 1.0000x reference)
.LBB0_124:
	s_or_b64 exec, exec, s[4:5]
	s_waitcnt vmcnt(0)
	s_barrier
	s_mov_b64 s[4:5], exec
	v_readlane_b32 s0, v219, 25
	v_readlane_b32 s1, v219, 26
	s_and_b64 s[0:1], s[4:5], s[0:1]
	s_mov_b64 exec, s[0:1]
	s_cbranch_execz .LBB0_176
	v_readlane_b32 s0, v219, 27
	v_readlane_b32 s1, v219, 28
	v_readlane_b32 s2, v219, 29
	v_mov_b32_e32 v0, 0x24000
	s_waitcnt vmcnt(0) lgkmcnt(0)
	buffer_inv sc1
	ds_read_b32 v2, v0
	ds_read_b32 v0, v0 offset:4
	s_lshl_b32 s3, s2, 8
	s_add_i32 s14, s3, 0x2400
	s_add_i32 s3, s3, 0x1400
	v_mov_b32_e32 v1, s3
	s_waitcnt lgkmcnt(0)
	v_readfirstlane_b32 s10, v2
	v_readfirstlane_b32 s11, v0
	v_mov_b32_e32 v0, 1
	s_nop 1
	global_atomic_add v2, v1, v0, s[0:1] sc0
	s_mul_i32 s10, s10, 2
	s_mul_i32 s11, s11, 2
	s_waitcnt vmcnt(0)
	v_readfirstlane_b32 s13, v2
	s_nop 1
	s_add_i32 s13, s13, 1
	s_cmp_lg_u32 s13, s10
	s_cbranch_scc1 .Lnb2_wait
	buffer_wbl2 sc1
	s_waitcnt vmcnt(0)
	v_mov_b32_e32 v1, 0x3400
	global_atomic_add v2, v1, v0, s[0:1] sc0
	s_waitcnt vmcnt(0)
	v_readfirstlane_b32 s13, v2
	s_nop 1
	s_add_i32 s13, s13, 1
	s_cmp_lg_u32 s13, s11
	s_cbranch_scc1 .Lnb2_wait
	v_mov_b32_e32 v1, 0x2400
	global_atomic_add v1, v0, s[0:1]
	global_atomic_add v1, v0, s[0:1] offset:256
	global_atomic_add v1, v0, s[0:1] offset:512
	global_atomic_add v1, v0, s[0:1] offset:768
	global_atomic_add v1, v0, s[0:1] offset:1024
	global_atomic_add v1, v0, s[0:1] offset:1280
	global_atomic_add v1, v0, s[0:1] offset:1536
	global_atomic_add v1, v0, s[0:1] offset:1792
	global_atomic_add v1, v0, s[0:1] offset:2048
	global_atomic_add v1, v0, s[0:1] offset:2304
	global_atomic_add v1, v0, s[0:1] offset:2560
	global_atomic_add v1, v0, s[0:1] offset:2816
	global_atomic_add v1, v0, s[0:1] offset:3072
	global_atomic_add v1, v0, s[0:1] offset:3328
	global_atomic_add v1, v0, s[0:1] offset:3584
	global_atomic_add v1, v0, s[0:1] offset:3840
	v_mov_b32_e32 v1, 0x3500
	global_atomic_add v1, v0, s[0:1]

.LBB0_577:
	s_or_b64 exec, exec, s[4:5]
	s_waitcnt vmcnt(0)
	s_barrier
	s_mov_b64 s[4:5], exec
	v_readlane_b32 s0, v219, 25
	v_readlane_b32 s1, v219, 26
	s_and_b64 s[0:1], s[4:5], s[0:1]
	s_mov_b64 exec, s[0:1]
	s_cbranch_execz .LBB0_629
	v_readlane_b32 s0, v219, 27
	v_readlane_b32 s1, v219, 28
	v_readlane_b32 s2, v219, 29
	v_mov_b32_e32 v0, 0x24000
	s_waitcnt vmcnt(0) lgkmcnt(0)
	buffer_inv sc1
	ds_read_b32 v2, v0
	ds_read_b32 v0, v0 offset:4
	s_lshl_b32 s3, s2, 8
	s_add_i32 s14, s3, 0x2400
	s_add_i32 s3, s3, 0x1400
	v_mov_b32_e32 v1, s3
	s_waitcnt lgkmcnt(0)
	v_readfirstlane_b32 s10, v2
	v_readfirstlane_b32 s11, v0
	v_mov_b32_e32 v0, 1
	s_nop 1
	global_atomic_add v2, v1, v0, s[0:1] sc0
	s_mul_i32 s10, s10, 6
	s_mul_i32 s11, s11, 6
	s_waitcnt vmcnt(0)
	v_readfirstlane_b32 s13, v2
	s_nop 1
	s_add_i32 s13, s13, 1
	s_cmp_lg_u32 s13, s10
	s_cbranch_scc1 .Lnb6_wait
	buffer_wbl2 sc1
	s_waitcnt vmcnt(0)
	v_mov_b32_e32 v1, 0x3400
	global_atomic_add v2, v1, v0, s[0:1] sc0
	s_waitcnt vmcnt(0)
	v_readfirstlane_b32 s13, v2
	s_nop 1
	s_add_i32 s13, s13, 1
	s_cmp_lg_u32 s13, s11
	s_cbranch_scc1 .Lnb6_wait
	v_mov_b32_e32 v1, 0x2400
	global_atomic_add v1, v0, s[0:1]
	global_atomic_add v1, v0, s[0:1] offset:256
	global_atomic_add v1, v0, s[0:1] offset:512
	global_atomic_add v1, v0, s[0:1] offset:768
	global_atomic_add v1, v0, s[0:1] offset:1024
	global_atomic_add v1, v0, s[0:1] offset:1280
	global_atomic_add v1, v0, s[0:1] offset:1536
	global_atomic_add v1, v0, s[0:1] offset:1792
	global_atomic_add v1, v0, s[0:1] offset:2048
	global_atomic_add v1, v0, s[0:1] offset:2304
	global_atomic_add v1, v0, s[0:1] offset:2560
	global_atomic_add v1, v0, s[0:1] offset:2816
	global_atomic_add v1, v0, s[0:1] offset:3072
	global_atomic_add v1, v0, s[0:1] offset:3328
	global_atomic_add v1, v0, s[0:1] offset:3584
	global_atomic_add v1, v0, s[0:1] offset:3840
	v_mov_b32_e32 v1, 0x3500
	global_atomic_add v1, v0, s[0:1]

.LBB0_866:
	s_or_b64 exec, exec, s[6:7]
	s_waitcnt vmcnt(0)
	s_barrier
	s_mov_b64 s[6:7], exec
	v_readlane_b32 s0, v219, 25
	v_readlane_b32 s1, v219, 26
	s_and_b64 s[0:1], s[6:7], s[0:1]
	s_mov_b64 exec, s[0:1]
	s_cbranch_execz .LBB0_918
	v_readlane_b32 s0, v219, 27
	v_readlane_b32 s1, v219, 28
	v_readlane_b32 s2, v219, 29
	v_mov_b32_e32 v0, 0x24000
	s_waitcnt vmcnt(0) lgkmcnt(0)
	buffer_inv sc1
	ds_read_b32 v2, v0
	ds_read_b32 v0, v0 offset:4
	s_lshl_b32 s3, s2, 8
	s_add_i32 s14, s3, 0x2400
	s_add_i32 s3, s3, 0x1400
	v_mov_b32_e32 v1, s3
	s_waitcnt lgkmcnt(0)
	v_readfirstlane_b32 s10, v2
	v_readfirstlane_b32 s11, v0
	v_mov_b32_e32 v0, 1
	s_nop 1
	global_atomic_add v2, v1, v0, s[0:1] sc0
	s_mul_i32 s10, s10, 9
	s_mul_i32 s11, s11, 9
	s_waitcnt vmcnt(0)
	v_readfirstlane_b32 s13, v2
	s_nop 1
	s_add_i32 s13, s13, 1
	s_cmp_lg_u32 s13, s10
	s_cbranch_scc1 .Lnb9_wait
	buffer_wbl2 sc1
	s_waitcnt vmcnt(0)
	v_mov_b32_e32 v1, 0x3400
	global_atomic_add v2, v1, v0, s[0:1] sc0
	s_waitcnt vmcnt(0)
	v_readfirstlane_b32 s13, v2
	s_nop 1
	s_add_i32 s13, s13, 1
	s_cmp_lg_u32 s13, s11
	s_cbranch_scc1 .Lnb9_wait
	v_mov_b32_e32 v1, 0x2400
	global_atomic_add v1, v0, s[0:1]
	global_atomic_add v1, v0, s[0:1] offset:256
	global_atomic_add v1, v0, s[0:1] offset:512
	global_atomic_add v1, v0, s[0:1] offset:768
	global_atomic_add v1, v0, s[0:1] offset:1024
	global_atomic_add v1, v0, s[0:1] offset:1280
	global_atomic_add v1, v0, s[0:1] offset:1536
	global_atomic_add v1, v0, s[0:1] offset:1792
	global_atomic_add v1, v0, s[0:1] offset:2048
	global_atomic_add v1, v0, s[0:1] offset:2304
	global_atomic_add v1, v0, s[0:1] offset:2560
	global_atomic_add v1, v0, s[0:1] offset:2816
	global_atomic_add v1, v0, s[0:1] offset:3072
	global_atomic_add v1, v0, s[0:1] offset:3328
	global_atomic_add v1, v0, s[0:1] offset:3584
	global_atomic_add v1, v0, s[0:1] offset:3840
	v_mov_b32_e32 v1, 0x3500
	global_atomic_add v1, v0, s[0:1]

.LBB0_1293:
	s_or_b64 exec, exec, s[6:7]
	s_waitcnt vmcnt(0)
	s_barrier
	s_mov_b64 s[6:7], exec
	v_readlane_b32 s0, v219, 25
	v_readlane_b32 s1, v219, 26
	s_and_b64 s[0:1], s[6:7], s[0:1]
	s_mov_b64 exec, s[0:1]
	s_cbranch_execz .LBB0_1345
	v_readlane_b32 s0, v219, 27
	v_readlane_b32 s1, v219, 28
	v_readlane_b32 s2, v219, 29
	v_mov_b32_e32 v0, 0x24000
	s_waitcnt vmcnt(0) lgkmcnt(0)
	buffer_inv sc1
	ds_read_b32 v2, v0
	ds_read_b32 v0, v0 offset:4
	s_lshl_b32 s3, s2, 8
	s_add_i32 s14, s3, 0x2400
	s_add_i32 s3, s3, 0x1400
	v_mov_b32_e32 v1, s3
	s_waitcnt lgkmcnt(0)
	v_readfirstlane_b32 s10, v2
	v_readfirstlane_b32 s11, v0
	v_mov_b32_e32 v0, 1
	s_nop 1
	global_atomic_add v2, v1, v0, s[0:1] sc0
	s_mul_i32 s10, s10, 13
	s_mul_i32 s11, s11, 13
	s_waitcnt vmcnt(0)
	v_readfirstlane_b32 s13, v2
	s_nop 1
	s_add_i32 s13, s13, 1
	s_cmp_lg_u32 s13, s10
	s_cbranch_scc1 .Lnb13_wait
	buffer_wbl2 sc1
	s_waitcnt vmcnt(0)
	v_mov_b32_e32 v1, 0x3400
	global_atomic_add v2, v1, v0, s[0:1] sc0
	s_waitcnt vmcnt(0)
	v_readfirstlane_b32 s13, v2
	s_nop 1
	s_add_i32 s13, s13, 1
	s_cmp_lg_u32 s13, s11
	s_cbranch_scc1 .Lnb13_wait
	v_mov_b32_e32 v1, 0x2400
	global_atomic_add v1, v0, s[0:1]
	global_atomic_add v1, v0, s[0:1] offset:256
	global_atomic_add v1, v0, s[0:1] offset:512
	global_atomic_add v1, v0, s[0:1] offset:768
	global_atomic_add v1, v0, s[0:1] offset:1024
	global_atomic_add v1, v0, s[0:1] offset:1280
	global_atomic_add v1, v0, s[0:1] offset:1536
	global_atomic_add v1, v0, s[0:1] offset:1792
	global_atomic_add v1, v0, s[0:1] offset:2048
	global_atomic_add v1, v0, s[0:1] offset:2304
	global_atomic_add v1, v0, s[0:1] offset:2560
	global_atomic_add v1, v0, s[0:1] offset:2816
	global_atomic_add v1, v0, s[0:1] offset:3072
	global_atomic_add v1, v0, s[0:1] offset:3328
	global_atomic_add v1, v0, s[0:1] offset:3584
	global_atomic_add v1, v0, s[0:1] offset:3840
	v_mov_b32_e32 v1, 0x3500
	global_atomic_add v1, v0, s[0:1]
